# F1 + grid barrier: the acquire-side cache invalidate is issued when the workgroup arrives (hidden under the barrier wait) instead of after the release
# speedup vs baseline: 1.0298x; 1.0298x over previous
.LBB1_143:
	s_or_b64 exec, exec, s[16:17]
	v_readlane_b32 s6, v254, 23
	v_readlane_b32 s7, v254, 24
	s_waitcnt vmcnt(0)
	s_nop 2
	global_atomic_add v113, v215, s[6:7]
	s_waitcnt vmcnt(0)

.LBB1_162:
	v_readlane_b32 s1, v255, 43
	s_add_i32 s1, s1, 2
	s_cmp_ge_i32 s1, s77
	s_cbranch_scc1 .LBB1_212
	s_waitcnt vmcnt(0)
	s_barrier
	s_mov_b64 s[2:3], exec
	v_readlane_b32 s6, v255, 20
	v_readlane_b32 s7, v255, 21
	s_and_b64 s[6:7], s[2:3], s[6:7]
	s_mov_b64 exec, s[6:7]
	s_cbranch_execz .LBB1_211
	v_readlane_b32 s5, v255, 18
	s_waitcnt vmcnt(0) expcnt(0) lgkmcnt(0)
	buffer_inv sc1
	s_nop 0
	v_mov_b32_e32 v0, s5
	ds_read_b32 v2, v0
	v_readlane_b32 s5, v255, 19
	s_waitcnt lgkmcnt(0)
	v_cmp_ne_u32_e32 vcc, 0, v2
	v_mov_b32_e32 v0, s5
	ds_read_b32 v0, v0
	s_cbranch_vccnz .LBB1_179
	v_readlane_b32 s10, v253, 8
	v_readlane_b32 s11, v253, 9
	s_load_dwordx2 s[6:7], s[10:11], 0x4
	s_waitcnt lgkmcnt(0)
	s_mul_i32 s5, s6, s33
	s_mul_i32 s5, s5, s7
	s_mov_b32 s6, 1
	s_branch .LBB1_167

.LBB1_192:
	s_or_b64 exec, exec, s[18:19]
	s_waitcnt vmcnt(0)
	s_waitcnt vmcnt(0)

.LBB1_295:
	v_readlane_b32 s1, v255, 43
	s_add_i32 s1, s1, 3
	s_cmp_lt_i32 s1, s77
	s_cselect_b64 s[16:17], -1, 0
	s_and_b64 s[2:3], s[2:3], s[16:17]
	s_andn2_b64 vcc, exec, s[2:3]
	s_cbranch_vccnz .LBB1_345
	s_waitcnt vmcnt(0)
	s_waitcnt vmcnt(0)
	s_barrier
	s_mov_b64 s[2:3], exec
	v_readlane_b32 s6, v255, 20
	v_readlane_b32 s7, v255, 21
	s_and_b64 s[6:7], s[2:3], s[6:7]
	s_mov_b64 exec, s[6:7]
	s_cbranch_execz .LBB1_344
	v_readlane_b32 s5, v255, 18
	s_waitcnt vmcnt(0) expcnt(0) lgkmcnt(0)
	buffer_inv sc1
	s_nop 0
	v_mov_b32_e32 v0, s5
	ds_read_b32 v2, v0
	v_readlane_b32 s5, v255, 19
	s_waitcnt lgkmcnt(0)
	v_cmp_ne_u32_e32 vcc, 0, v2
	v_mov_b32_e32 v0, s5
	ds_read_b32 v0, v0
	s_cbranch_vccnz .LBB1_312
	v_readlane_b32 s10, v253, 8
	v_readlane_b32 s11, v253, 9
	s_load_dwordx2 s[6:7], s[10:11], 0x4
	s_waitcnt lgkmcnt(0)
	s_mul_i32 s5, s6, s33
	s_mul_i32 s5, s5, s7
	s_mov_b32 s6, 1
	s_branch .LBB1_300

.LBB1_325:
	s_or_b64 exec, exec, s[26:27]
	s_waitcnt vmcnt(0)
	s_waitcnt vmcnt(0)

.LBB1_343:
	s_or_b64 exec, exec, s[18:19]
	v_readlane_b32 s6, v254, 23
	v_readlane_b32 s7, v254, 24
	s_waitcnt vmcnt(0)
	s_nop 2
	global_atomic_add v113, v215, s[6:7]
	s_waitcnt vmcnt(0)

.LBB1_418:
	v_readlane_b32 s1, v255, 43
	s_add_i32 s1, s1, 4
	s_cmp_ge_i32 s1, s77
	s_cbranch_scc1 .LBB1_468
	s_waitcnt vmcnt(0)
	s_waitcnt vmcnt(0)
	s_barrier
	s_mov_b64 s[2:3], exec
	v_readlane_b32 s6, v255, 20
	v_readlane_b32 s7, v255, 21
	s_and_b64 s[6:7], s[2:3], s[6:7]
	s_mov_b64 exec, s[6:7]
	s_cbranch_execz .LBB1_467
	v_readlane_b32 s5, v255, 18
	s_waitcnt vmcnt(0) expcnt(0) lgkmcnt(0)
	buffer_inv sc1
	s_nop 0
	v_mov_b32_e32 v0, s5
	ds_read_b32 v2, v0
	v_readlane_b32 s5, v255, 19
	s_waitcnt lgkmcnt(0)
	v_cmp_ne_u32_e32 vcc, 0, v2
	v_mov_b32_e32 v0, s5
	ds_read_b32 v0, v0
	s_cbranch_vccnz .LBB1_435
	v_readlane_b32 s10, v253, 8
	v_readlane_b32 s11, v253, 9
	s_load_dwordx2 s[6:7], s[10:11], 0x4
	s_waitcnt lgkmcnt(0)
	s_mul_i32 s5, s6, s33
	s_mul_i32 s5, s5, s7
	s_mov_b32 s6, 1
	s_branch .LBB1_423

.LBB1_553:
	v_readlane_b32 s1, v255, 43
	s_add_i32 s1, s1, 5
	s_cmp_ge_i32 s1, s77
	s_cbranch_scc1 .LBB1_603
	s_waitcnt vmcnt(0)
	s_waitcnt vmcnt(0)
	s_barrier
	s_mov_b64 s[2:3], exec
	v_readlane_b32 s6, v255, 20
	v_readlane_b32 s7, v255, 21
	s_and_b64 s[6:7], s[2:3], s[6:7]
	s_mov_b64 exec, s[6:7]
	s_cbranch_execz .LBB1_602
	v_readlane_b32 s5, v255, 18
	s_waitcnt vmcnt(0) expcnt(0) lgkmcnt(0)
	buffer_inv sc1
	s_nop 0
	v_mov_b32_e32 v0, s5
	ds_read_b32 v2, v0
	v_readlane_b32 s5, v255, 19
	s_waitcnt lgkmcnt(0)
	v_cmp_ne_u32_e32 vcc, 0, v2
	v_mov_b32_e32 v0, s5
	ds_read_b32 v0, v0
	s_cbranch_vccnz .LBB1_570
	v_readlane_b32 s10, v253, 8
	v_readlane_b32 s11, v253, 9
	s_load_dwordx2 s[6:7], s[10:11], 0x4
	s_waitcnt lgkmcnt(0)
	s_mul_i32 s5, s6, s33
	s_mul_i32 s5, s5, s7
	s_mov_b32 s6, 1
	s_branch .LBB1_558

.LBB1_651:
	v_readlane_b32 s1, v255, 43
	s_add_i32 s1, s1, 6
	s_cmp_lt_i32 s1, s77
	s_cselect_b64 s[16:17], -1, 0
	s_and_b64 s[2:3], s[42:43], s[16:17]
	s_andn2_b64 vcc, exec, s[2:3]
	s_cbranch_vccnz .LBB1_701
	s_waitcnt vmcnt(0)
	s_waitcnt vmcnt(0)
	s_barrier
	s_mov_b64 s[2:3], exec
	v_readlane_b32 s6, v255, 20
	v_readlane_b32 s7, v255, 21
	s_and_b64 s[6:7], s[2:3], s[6:7]
	s_mov_b64 exec, s[6:7]
	s_cbranch_execz .LBB1_700
	v_readlane_b32 s5, v255, 18
	s_waitcnt vmcnt(0) expcnt(0) lgkmcnt(0)
	buffer_inv sc1
	s_nop 0
	v_mov_b32_e32 v0, s5
	ds_read_b32 v2, v0
	v_readlane_b32 s5, v255, 19
	s_waitcnt lgkmcnt(0)
	v_cmp_ne_u32_e32 vcc, 0, v2
	v_mov_b32_e32 v0, s5
	ds_read_b32 v0, v0
	s_cbranch_vccnz .LBB1_668
	v_readlane_b32 s10, v253, 8
	v_readlane_b32 s11, v253, 9
	s_load_dwordx2 s[6:7], s[10:11], 0x4
	s_waitcnt lgkmcnt(0)
	s_mul_i32 s5, s6, s33
	s_mul_i32 s5, s5, s7
	s_mov_b32 s6, 1
	s_branch .LBB1_656

.LBB1_815:
	v_readlane_b32 s1, v255, 43
	s_add_i32 s1, s1, 7
	s_cmp_lt_i32 s1, s77
	s_cselect_b64 s[16:17], -1, 0
	s_and_b64 s[2:3], s[2:3], s[16:17]
	s_andn2_b64 vcc, exec, s[2:3]
	s_cbranch_vccnz .LBB1_865
	s_waitcnt vmcnt(0)
	s_waitcnt vmcnt(0)
	s_barrier
	s_mov_b64 s[2:3], exec
	v_readlane_b32 s6, v255, 20
	v_readlane_b32 s7, v255, 21
	s_and_b64 s[6:7], s[2:3], s[6:7]
	s_mov_b64 exec, s[6:7]
	s_cbranch_execz .LBB1_864
	v_readlane_b32 s5, v255, 18
	s_waitcnt vmcnt(0) expcnt(0) lgkmcnt(0)
	buffer_inv sc1
	s_nop 0
	v_mov_b32_e32 v0, s5
	ds_read_b32 v2, v0
	v_readlane_b32 s5, v255, 19
	s_waitcnt lgkmcnt(0)
	v_cmp_ne_u32_e32 vcc, 0, v2
	v_mov_b32_e32 v0, s5
	ds_read_b32 v0, v0
	s_cbranch_vccnz .LBB1_832
	v_readlane_b32 s10, v253, 8
	v_readlane_b32 s11, v253, 9
	s_load_dwordx2 s[6:7], s[10:11], 0x4
	s_waitcnt lgkmcnt(0)
	s_mul_i32 s5, s6, s33
	s_mul_i32 s5, s5, s7
	s_mov_b32 s6, 1
	s_branch .LBB1_820

.LBB1_873:
	v_readlane_b32 s1, v255, 43
	s_add_i32 s1, s1, 8
	s_cmp_ge_i32 s1, s77
	s_cbranch_scc1 .LBB1_885
	s_waitcnt vmcnt(0)
	s_waitcnt vmcnt(0)
	s_barrier
	s_mov_b64 s[2:3], exec
	v_readlane_b32 s6, v255, 20
	v_readlane_b32 s7, v255, 21
	s_and_b64 s[6:7], s[2:3], s[6:7]
	s_movk_i32 s25, 0x120
	s_mov_b64 exec, s[6:7]
	s_cbranch_execz .LBB1_923
	v_readlane_b32 s5, v255, 18
	s_waitcnt vmcnt(0) expcnt(0) lgkmcnt(0)
	buffer_inv sc1
	s_nop 0
	v_mov_b32_e32 v0, s5
	ds_read_b32 v2, v0
	v_readlane_b32 s5, v255, 19
	s_waitcnt lgkmcnt(0)
	v_cmp_ne_u32_e32 vcc, 0, v2
	v_mov_b32_e32 v0, s5
	ds_read_b32 v0, v0
	s_cbranch_vccnz .LBB1_891
	v_readlane_b32 s10, v253, 8
	v_readlane_b32 s11, v253, 9
	s_load_dwordx2 s[6:7], s[10:11], 0x4
	s_waitcnt lgkmcnt(0)
	s_mul_i32 s5, s6, s33
	s_mul_i32 s5, s5, s7
	s_mov_b32 s6, 1
	s_branch .LBB1_878

.LBB1_1126:
	v_readlane_b32 s56, v253, 42
	v_readlane_b32 s1, v255, 43
	v_readlane_b32 s57, v253, 43
	s_add_i32 s1, s1, 9
	s_mov_b64 s[76:77], s[56:57]
	s_cmp_lt_i32 s1, s77
	v_readlane_b32 s2, v255, 45
	s_cselect_b64 s[16:17], -1, 0
	v_readlane_b32 s3, v255, 46
	s_and_b64 s[2:3], s[2:3], s[16:17]
	s_andn2_b64 vcc, exec, s[2:3]
	v_readlane_b32 s58, v253, 44
	v_readlane_b32 s59, v253, 45
	s_cbranch_vccnz .LBB1_1176
	s_waitcnt vmcnt(0)
	s_waitcnt vmcnt(0) lgkmcnt(0)
	s_barrier
	s_mov_b64 s[2:3], exec
	v_readlane_b32 s6, v255, 20
	v_readlane_b32 s7, v255, 21
	s_and_b64 s[6:7], s[2:3], s[6:7]
	s_mov_b64 exec, s[6:7]
	s_cbranch_execz .LBB1_1175
	v_readlane_b32 s5, v255, 18
	s_waitcnt vmcnt(0) expcnt(0) lgkmcnt(0)
	buffer_inv sc1
	s_nop 0
	v_mov_b32_e32 v0, s5
	ds_read_b32 v2, v0
	v_readlane_b32 s5, v255, 19
	s_waitcnt lgkmcnt(0)
	v_cmp_ne_u32_e32 vcc, 0, v2
	v_mov_b32_e32 v0, s5
	ds_read_b32 v0, v0
	s_cbranch_vccnz .LBB1_1143
	v_readlane_b32 s10, v253, 8
	v_readlane_b32 s11, v253, 9
	s_load_dwordx2 s[6:7], s[10:11], 0x4
	s_waitcnt lgkmcnt(0)
	s_mul_i32 s5, s6, s33
	s_mul_i32 s5, s5, s7
	s_mov_b32 s6, 1
	s_branch .LBB1_1131

.LBB1_1186:
	s_or_b64 exec, exec, s[2:3]
	v_readlane_b32 s1, v255, 43
	s_add_i32 s1, s1, 10
	s_cmp_ge_i32 s1, s77
	s_cbranch_scc1 .LBB1_1236
	s_waitcnt vmcnt(0)
	s_waitcnt vmcnt(0) lgkmcnt(0)
	s_barrier
	s_mov_b64 s[2:3], exec
	v_readlane_b32 s6, v255, 20
	v_readlane_b32 s7, v255, 21
	s_and_b64 s[6:7], s[2:3], s[6:7]
	s_mov_b64 exec, s[6:7]
	s_cbranch_execz .LBB1_1235
	v_readlane_b32 s5, v255, 18
	s_waitcnt vmcnt(0) expcnt(0) lgkmcnt(0)
	buffer_inv sc1
	s_nop 0
	v_mov_b32_e32 v0, s5
	ds_read_b32 v2, v0
	v_readlane_b32 s5, v255, 19
	s_waitcnt lgkmcnt(0)
	v_cmp_ne_u32_e32 vcc, 0, v2
	v_mov_b32_e32 v0, s5
	ds_read_b32 v0, v0
	s_cbranch_vccnz .LBB1_1203
	v_readlane_b32 s10, v253, 8
	v_readlane_b32 s11, v253, 9
	s_load_dwordx2 s[6:7], s[10:11], 0x4
	s_waitcnt lgkmcnt(0)
	s_mul_i32 s5, s6, s33
	s_mul_i32 s5, s5, s7
	s_mov_b32 s6, 1
	s_branch .LBB1_1191

.LBB1_1270:
	v_readlane_b32 s1, v255, 18
	s_waitcnt vmcnt(0) expcnt(0) lgkmcnt(0)
	buffer_inv sc1
	s_nop 0
	v_mov_b32_e32 v0, s1
	ds_read_b32 v2, v0
	v_readlane_b32 s1, v255, 19
	s_waitcnt lgkmcnt(0)
	v_cmp_ne_u32_e32 vcc, 0, v2
	v_mov_b32_e32 v0, s1
	ds_read_b32 v0, v0
	s_cbranch_vccnz .LBB1_1285
	v_readlane_b32 s10, v253, 8
	v_readlane_b32 s11, v253, 9
	s_load_dwordx2 s[6:7], s[10:11], 0x4
	s_mov_b32 s5, 1
	s_waitcnt lgkmcnt(0)
	s_mul_i32 s1, s6, s33
	s_mul_i32 s1, s1, s7
	s_branch .LBB1_1273
